# merge epilogue PROJ loads hoisted + gate_unit u loads hoisted before barrier (counted vmcnt)
# speedup vs baseline: 1.0161x; 1.0073x over previous
.LBB0_903:
	s_load_dwordx4 s[4:7], s[0:1], 0x60
	s_load_dwordx2 s[12:13], s[0:1], 0x78
	s_and_b32 s11, s63, 3
	s_lshl_b64 s[16:17], s[72:73], 2
	v_ashrrev_i32_e32 v44, 2, v188
	s_waitcnt lgkmcnt(0)
	s_add_u32 s4, s4, s16
	s_addc_u32 s5, s5, s17
	s_lshl_b32 s18, s11, 9
	s_add_u32 s8, s4, s18
	s_addc_u32 s9, s5, 0
	s_add_u32 s4, s6, s16
	s_addc_u32 s5, s7, s17
	s_add_u32 s6, s4, s18
	s_addc_u32 s7, s5, 0
	s_add_u32 s4, s12, s16
	v_add_u32_e32 v2, s10, v44
	s_addc_u32 s5, s13, s17
	v_ashrrev_i32_e32 v3, 31, v2
	s_add_u32 s4, s4, s18
	v_lshlrev_b32_e32 v0, 5, v188
	v_lshl_add_u64 v[4:5], v[2:3], 3, s[84:85]
	v_lshlrev_b64 v[2:3], 13, v[2:3]
	s_addc_u32 s5, s5, 0
	v_and_b32_e32 v18, 0x60, v0
	v_lshl_add_u64 v[2:3], s[82:83], 0, v[2:3]
	s_lshl_b32 s40, s11, 8
	v_lshl_add_u64 v[2:3], v[2:3], 0, s[40:41]
	v_lshlrev_b32_e32 v0, 1, v18
	v_lshl_add_u64 v[2:3], v[2:3], 0, v[0:1]
	s_mov_b64 s[12:13], 0x1000
	global_load_dwordx2 v[42:43], v[4:5], off
	v_lshl_add_u64 v[14:15], v[2:3], 0, s[12:13]
	v_add_co_u32_e32 v2, vcc, s44, v2
	v_lshlrev_b32_e32 v56, 2, v18
	s_nop 0
	v_addc_co_u32_e32 v3, vcc, 0, v3, vcc
	global_load_dwordx4 v[10:13], v[2:3], off
	s_nop 0
	global_load_dwordx4 v[2:5], v[14:15], off offset:48
	global_load_dwordx4 v[6:9], v[14:15], off offset:32
	s_nop 0
	global_load_dwordx4 v[14:17], v[14:15], off offset:16
	s_nop 0
	global_load_dwordx4 v[18:21], v56, s[8:9] offset:48
	global_load_dwordx4 v[22:25], v56, s[8:9] offset:32
	global_load_dwordx4 v[26:29], v56, s[8:9] offset:16
	global_load_dwordx4 v[30:33], v56, s[8:9]
	global_load_dwordx4 v[34:37], v56, s[6:7] offset:48
	global_load_dwordx4 v[38:41], v56, s[6:7] offset:32
	global_load_dwordx4 v[46:49], v56, s[6:7] offset:16
	global_load_dwordx4 v[50:53], v56, s[6:7]
	v_mul_lo_u32 v45, v44, s46
	v_add3_u32 v0, 0, v45, v0
	s_waitcnt vmcnt(11)
	v_lshlrev_b32_e32 v54, 16, v10
	v_and_b32_e32 v55, 0xffff0000, v10
	v_pk_add_f32 v[54:55], v[54:55], v[42:43] op_sel_hi:[1,0] neg_lo:[0,1] neg_hi:[0,1]
	s_nop 0
	v_pk_mul_f32 v[54:55], v[42:43], v[54:55] op_sel:[1,0]
	s_waitcnt vmcnt(0)
	v_pk_fma_f32 v[30:31], v[30:31], v[54:55], v[50:51]
	s_nop 0
	v_cvt_pk_bf16_f32 v10, v30, v31
	v_lshlrev_b32_e32 v30, 16, v11
	v_and_b32_e32 v31, 0xffff0000, v11
	v_pk_add_f32 v[30:31], v[30:31], v[42:43] op_sel_hi:[1,0] neg_lo:[0,1] neg_hi:[0,1]
	s_nop 0
	v_pk_mul_f32 v[30:31], v[42:43], v[30:31] op_sel:[1,0]
	s_nop 0
	v_pk_fma_f32 v[30:31], v[32:33], v[30:31], v[52:53]
	s_nop 0
	v_cvt_pk_bf16_f32 v11, v30, v31
	v_lshlrev_b32_e32 v30, 16, v12
	v_and_b32_e32 v31, 0xffff0000, v12
	v_pk_add_f32 v[30:31], v[30:31], v[42:43] op_sel_hi:[1,0] neg_lo:[0,1] neg_hi:[0,1]
	s_nop 0
	v_pk_mul_f32 v[30:31], v[42:43], v[30:31] op_sel:[1,0]
	s_nop 0
	v_pk_fma_f32 v[26:27], v[26:27], v[30:31], v[46:47]
	v_lshlrev_b32_e32 v46, 16, v6
	v_cvt_pk_bf16_f32 v12, v26, v27
	v_lshlrev_b32_e32 v26, 16, v13
	v_and_b32_e32 v27, 0xffff0000, v13
	v_pk_add_f32 v[26:27], v[26:27], v[42:43] op_sel_hi:[1,0] neg_lo:[0,1] neg_hi:[0,1]
	v_and_b32_e32 v47, 0xffff0000, v6
	v_pk_mul_f32 v[26:27], v[42:43], v[26:27] op_sel:[1,0]
	v_pk_add_f32 v[46:47], v[46:47], v[42:43] op_sel_hi:[1,0] neg_lo:[0,1] neg_hi:[0,1]
	v_pk_fma_f32 v[26:27], v[28:29], v[26:27], v[48:49]
	v_pk_mul_f32 v[46:47], v[42:43], v[46:47] op_sel:[1,0]
	v_cvt_pk_bf16_f32 v13, v26, v27
	ds_write_b128 v0, v[10:13]
	v_lshlrev_b32_e32 v10, 16, v14
	v_and_b32_e32 v11, 0xffff0000, v14
	v_lshlrev_b32_e32 v12, 16, v15
	v_and_b32_e32 v13, 0xffff0000, v15
	v_pk_add_f32 v[10:11], v[10:11], v[42:43] op_sel_hi:[1,0] neg_lo:[0,1] neg_hi:[0,1]
	v_pk_add_f32 v[12:13], v[12:13], v[42:43] op_sel_hi:[1,0] neg_lo:[0,1] neg_hi:[0,1]
	v_pk_mul_f32 v[10:11], v[42:43], v[10:11] op_sel:[1,0]
	v_pk_mul_f32 v[12:13], v[42:43], v[12:13] op_sel:[1,0]
	v_pk_fma_f32 v[10:11], v[22:23], v[10:11], v[38:39]
	v_pk_fma_f32 v[12:13], v[24:25], v[12:13], v[40:41]
	v_cvt_pk_bf16_f32 v10, v10, v11
	v_cvt_pk_bf16_f32 v11, v12, v13
	v_lshlrev_b32_e32 v12, 16, v16
	v_and_b32_e32 v13, 0xffff0000, v16
	v_lshlrev_b32_e32 v14, 16, v17
	v_and_b32_e32 v15, 0xffff0000, v17
	v_pk_add_f32 v[12:13], v[12:13], v[42:43] op_sel_hi:[1,0] neg_lo:[0,1] neg_hi:[0,1]
	v_pk_add_f32 v[14:15], v[14:15], v[42:43] op_sel_hi:[1,0] neg_lo:[0,1] neg_hi:[0,1]
	v_pk_mul_f32 v[12:13], v[42:43], v[12:13] op_sel:[1,0]
	v_pk_mul_f32 v[14:15], v[42:43], v[14:15] op_sel:[1,0]
	v_pk_fma_f32 v[12:13], v[18:19], v[12:13], v[34:35]
	v_pk_fma_f32 v[14:15], v[20:21], v[14:15], v[36:37]
	v_cvt_pk_bf16_f32 v12, v12, v13
	v_cvt_pk_bf16_f32 v13, v14, v15
	ds_write_b128 v0, v[10:13] offset:16
	global_load_dwordx4 v[10:13], v56, s[8:9] offset:112
	global_load_dwordx4 v[18:21], v56, s[8:9] offset:96
	global_load_dwordx4 v[26:29], v56, s[8:9] offset:80
	global_load_dwordx4 v[34:37], v56, s[8:9] offset:64
	global_load_dwordx4 v[14:17], v56, s[6:7] offset:112
	global_load_dwordx4 v[22:25], v56, s[6:7] offset:96
	global_load_dwordx4 v[30:33], v56, s[6:7] offset:80
	global_load_dwordx4 v[38:41], v56, s[6:7] offset:64
	s_lshl_b32 s6, s11, 15
	v_readlane_b32 s7, v255, 33
	s_add_u32 s6, s7, s6
	v_readlane_b32 s7, v255, 34
	s_addc_u32 s7, s7, 0
	s_mov_b32 s8, 4
	s_waitcnt vmcnt(0)
	v_pk_fma_f32 v[34:35], v[34:35], v[46:47], v[38:39]
	s_nop 0
	v_cvt_pk_bf16_f32 v6, v34, v35
	v_lshlrev_b32_e32 v34, 16, v7
	v_and_b32_e32 v35, 0xffff0000, v7
	v_pk_add_f32 v[34:35], v[34:35], v[42:43] op_sel_hi:[1,0] neg_lo:[0,1] neg_hi:[0,1]
	s_nop 0
	v_pk_mul_f32 v[34:35], v[42:43], v[34:35] op_sel:[1,0]
	s_nop 0
	v_pk_fma_f32 v[34:35], v[36:37], v[34:35], v[40:41]
	s_nop 0
	v_cvt_pk_bf16_f32 v7, v34, v35
	v_lshlrev_b32_e32 v34, 16, v8
	v_and_b32_e32 v35, 0xffff0000, v8
	v_pk_add_f32 v[34:35], v[34:35], v[42:43] op_sel_hi:[1,0] neg_lo:[0,1] neg_hi:[0,1]
	s_nop 0
	v_pk_mul_f32 v[34:35], v[42:43], v[34:35] op_sel:[1,0]
	s_nop 0
	v_pk_fma_f32 v[26:27], v[26:27], v[34:35], v[30:31]
	s_nop 0
	v_cvt_pk_bf16_f32 v8, v26, v27
	v_lshlrev_b32_e32 v26, 16, v9
	v_and_b32_e32 v27, 0xffff0000, v9
	v_pk_add_f32 v[26:27], v[26:27], v[42:43] op_sel_hi:[1,0] neg_lo:[0,1] neg_hi:[0,1]
	s_nop 0
	v_pk_mul_f32 v[26:27], v[42:43], v[26:27] op_sel:[1,0]
	s_nop 0
	v_pk_fma_f32 v[26:27], v[28:29], v[26:27], v[32:33]
	s_nop 0
	v_cvt_pk_bf16_f32 v9, v26, v27
	ds_write_b128 v0, v[6:9] offset:32
	v_lshlrev_b32_e32 v6, 16, v2
	v_and_b32_e32 v7, 0xffff0000, v2
	v_pk_add_f32 v[6:7], v[6:7], v[42:43] op_sel_hi:[1,0] neg_lo:[0,1] neg_hi:[0,1]
	s_nop 0
	v_pk_mul_f32 v[6:7], v[42:43], v[6:7] op_sel:[1,0]
	s_nop 0
	v_pk_fma_f32 v[6:7], v[18:19], v[6:7], v[22:23]
	v_bfi_b32 v18, -16, v44, v188
	v_cvt_pk_bf16_f32 v2, v6, v7
	v_lshlrev_b32_e32 v6, 16, v3
	v_and_b32_e32 v7, 0xffff0000, v3
	v_pk_add_f32 v[6:7], v[6:7], v[42:43] op_sel_hi:[1,0] neg_lo:[0,1] neg_hi:[0,1]
	v_ashrrev_i32_e32 v19, 31, v18
	v_pk_mul_f32 v[6:7], v[42:43], v[6:7] op_sel:[1,0]
	s_nop 0
	v_pk_fma_f32 v[6:7], v[20:21], v[6:7], v[24:25]
	v_add_u32_e32 v20, s10, v18
	v_cvt_pk_bf16_f32 v3, v6, v7
	v_lshlrev_b32_e32 v6, 16, v4
	v_and_b32_e32 v7, 0xffff0000, v4
	v_pk_add_f32 v[6:7], v[6:7], v[42:43] op_sel_hi:[1,0] neg_lo:[0,1] neg_hi:[0,1]
	v_ashrrev_i32_e32 v21, 31, v20
	v_pk_mul_f32 v[6:7], v[42:43], v[6:7] op_sel:[1,0]
	s_nop 0
	v_pk_fma_f32 v[6:7], v[10:11], v[6:7], v[14:15]
	s_nop 0
	v_cvt_pk_bf16_f32 v4, v6, v7
	v_lshlrev_b32_e32 v6, 16, v5
	v_and_b32_e32 v7, 0xffff0000, v5
	v_pk_add_f32 v[6:7], v[6:7], v[42:43] op_sel_hi:[1,0] neg_lo:[0,1] neg_hi:[0,1]
	s_nop 0
	v_pk_mul_f32 v[6:7], v[42:43], v[6:7] op_sel:[1,0]
	s_nop 0
	v_pk_fma_f32 v[6:7], v[12:13], v[6:7], v[16:17]
	s_nop 0
	v_cvt_pk_bf16_f32 v5, v6, v7
	ds_write_b128 v0, v[2:5] offset:48
	v_bfe_u32 v0, v188, 4, 2
	v_lshlrev_b64 v[2:3], 8, v[18:19]
	v_lshl_add_u64 v[2:3], s[6:7], 0, v[2:3]
	v_lshlrev_b32_e32 v32, 3, v0
	v_lshlrev_b32_e32 v0, 4, v0
	v_lshl_add_u64 v[10:11], v[2:3], 0, v[0:1]
	global_load_dwordx4 v[2:5], v[10:11], off
	global_load_dwordx4 v[6:9], v[10:11], off offset:64
	global_load_dwordx4 v[14:17], v[10:11], off offset:128
	s_nop 0
	global_load_dwordx4 v[10:13], v[10:11], off offset:192
	v_lshl_add_u64 v[18:19], v[18:19], 2, s[4:5]
	v_bfe_u32 v0, v188, 2, 2
	global_load_dword v22, v[18:19], off
	v_lshlrev_b64 v[76:77], 13, v[20:21]
	v_lshl_add_u64 v[76:77], s[82:83], 0, v[76:77]
	v_or_b32_e32 v78, s40, v32
	v_mov_b32_e32 v79, 0
	v_lshl_add_u64 v[76:77], v[76:77], 0, v[78:79]
	global_load_dwordx2 v[60:61], v[76:77], off offset:3072
	global_load_dwordx2 v[62:63], v[76:77], off offset:3104
	global_load_dwordx2 v[64:65], v[76:77], off offset:3136
	global_load_dwordx2 v[66:67], v[76:77], off offset:3168
	global_load_dwordx2 v[68:69], v[76:77], off offset:3200
	global_load_dwordx2 v[70:71], v[76:77], off offset:3232
	global_load_dwordx2 v[72:73], v[76:77], off offset:3264
	global_load_dwordx2 v[74:75], v[76:77], off offset:3296
	v_or_b32_e32 v0, v32, v0
	v_lshlrev_b32_e32 v18, 3, v188
	v_and_b32_e32 v23, 24, v18
	v_lshlrev_b64 v[18:19], 13, v[20:21]
	v_mul_u32_u24_e32 v0, 0x110, v0
	s_waitcnt lgkmcnt(0)
	s_barrier
	v_lshl_add_u64 v[28:29], s[82:83], 0, v[18:19]
	v_lshlrev_b64 v[18:19], 10, v[20:21]
	v_add3_u32 v23, 0, v23, v0
	v_lshl_add_u64 v[30:31], s[86:87], 0, v[18:19]
	ds_read_b64_tr_b16 v[18:19], v23
	ds_read_b64_tr_b16 v[20:21], v23 offset:1088
	ds_read_b64_tr_b16 v[24:25], v23 offset:8704
	ds_read_b64_tr_b16 v[26:27], v23 offset:9792
	s_waitcnt vmcnt(12) lgkmcnt(2)
	v_mfma_f32_16x16x32_bf16 v[18:21], v[18:21], v[2:5], 0
	v_or_b32_e32 v0, s40, v32
	s_waitcnt vmcnt(11) lgkmcnt(0)
	v_mfma_f32_16x16x32_bf16 v[18:21], v[24:27], v[6:9], v[18:21]
	ds_read_b64_tr_b16 v[24:25], v23 offset:17408
	ds_read_b64_tr_b16 v[26:27], v23 offset:18496
	s_waitcnt vmcnt(10) lgkmcnt(0)
	v_mfma_f32_16x16x32_bf16 v[18:21], v[24:27], v[14:17], v[18:21]
	ds_read_b64_tr_b16 v[24:25], v23 offset:26112
	ds_read_b64_tr_b16 v[26:27], v23 offset:27200
	s_waitcnt vmcnt(9) lgkmcnt(0)
	v_mfma_f32_16x16x32_bf16 v[18:21], v[24:27], v[10:13], v[18:21]
	v_lshl_add_u64 v[26:27], v[28:29], 0, v[0:1]
	s_nop 0
	s_waitcnt vmcnt(7)
	v_lshlrev_b32_e32 v28, 16, v60
	v_and_b32_e32 v29, 0xffff0000, v60
	s_nop 2
	v_pk_add_f32 v[18:19], v[22:23], v[18:19] op_sel_hi:[0,1]
	v_lshlrev_b32_e32 v24, 16, v61
	v_and_b32_e32 v25, 0xffff0000, v61
	v_pk_add_f32 v[20:21], v[22:23], v[20:21] op_sel_hi:[0,1]
	v_pk_mul_f32 v[18:19], v[18:19], v[28:29]
	v_pk_mul_f32 v[20:21], v[20:21], v[24:25]
	v_cvt_pk_bf16_f32 v18, v18, v19
	v_cvt_pk_bf16_f32 v19, v20, v21
	v_lshl_add_u64 v[24:25], v[30:31], 0, v[0:1]
	global_store_dwordx2 v[24:25], v[18:19], off
	ds_read_b64_tr_b16 v[18:19], v23 offset:32
	ds_read_b64_tr_b16 v[20:21], v23 offset:1120
	ds_read_b64_tr_b16 v[28:29], v23 offset:8736
	ds_read_b64_tr_b16 v[30:31], v23 offset:9824
	s_waitcnt lgkmcnt(2)
	v_mfma_f32_16x16x32_bf16 v[18:21], v[18:21], v[2:5], 0
	s_waitcnt lgkmcnt(0)
	v_mfma_f32_16x16x32_bf16 v[18:21], v[28:31], v[6:9], v[18:21]
	ds_read_b64_tr_b16 v[28:29], v23 offset:17440
	ds_read_b64_tr_b16 v[30:31], v23 offset:18528
	s_waitcnt lgkmcnt(0)
	v_mfma_f32_16x16x32_bf16 v[18:21], v[28:31], v[14:17], v[18:21]
	ds_read_b64_tr_b16 v[28:29], v23 offset:26144
	ds_read_b64_tr_b16 v[30:31], v23 offset:27232
	s_waitcnt lgkmcnt(0)
	v_mfma_f32_16x16x32_bf16 v[18:21], v[28:31], v[10:13], v[18:21]
	s_nop 0
	s_waitcnt vmcnt(7)
	v_lshlrev_b32_e32 v30, 16, v62
	v_and_b32_e32 v31, 0xffff0000, v62
	s_nop 3
	v_pk_add_f32 v[18:19], v[22:23], v[18:19] op_sel_hi:[0,1]
	v_lshlrev_b32_e32 v28, 16, v63
	v_and_b32_e32 v29, 0xffff0000, v63
	v_pk_add_f32 v[20:21], v[22:23], v[20:21] op_sel_hi:[0,1]
	v_pk_mul_f32 v[18:19], v[18:19], v[30:31]
	v_pk_mul_f32 v[20:21], v[20:21], v[28:29]
	v_cvt_pk_bf16_f32 v18, v18, v19
	v_cvt_pk_bf16_f32 v19, v20, v21
	global_store_dwordx2 v[24:25], v[18:19], off offset:32
	ds_read_b64_tr_b16 v[18:19], v23 offset:64
	ds_read_b64_tr_b16 v[20:21], v23 offset:1152
	ds_read_b64_tr_b16 v[28:29], v23 offset:8768
	ds_read_b64_tr_b16 v[30:31], v23 offset:9856
	s_waitcnt lgkmcnt(2)
	v_mfma_f32_16x16x32_bf16 v[18:21], v[18:21], v[2:5], 0
	s_waitcnt lgkmcnt(0)
	v_mfma_f32_16x16x32_bf16 v[18:21], v[28:31], v[6:9], v[18:21]
	ds_read_b64_tr_b16 v[28:29], v23 offset:17472
	ds_read_b64_tr_b16 v[30:31], v23 offset:18560
	s_waitcnt lgkmcnt(0)
	v_mfma_f32_16x16x32_bf16 v[18:21], v[28:31], v[14:17], v[18:21]
	ds_read_b64_tr_b16 v[28:29], v23 offset:26176
	ds_read_b64_tr_b16 v[30:31], v23 offset:27264
	s_waitcnt lgkmcnt(0)
	v_mfma_f32_16x16x32_bf16 v[18:21], v[28:31], v[10:13], v[18:21]
	s_nop 0
	s_waitcnt vmcnt(7)
	v_lshlrev_b32_e32 v30, 16, v64
	v_and_b32_e32 v31, 0xffff0000, v64
	s_nop 3
	v_pk_add_f32 v[18:19], v[22:23], v[18:19] op_sel_hi:[0,1]
	v_lshlrev_b32_e32 v28, 16, v65
	v_and_b32_e32 v29, 0xffff0000, v65
	v_pk_add_f32 v[20:21], v[22:23], v[20:21] op_sel_hi:[0,1]
	v_pk_mul_f32 v[18:19], v[18:19], v[30:31]
	v_pk_mul_f32 v[20:21], v[20:21], v[28:29]
	v_cvt_pk_bf16_f32 v18, v18, v19
	v_cvt_pk_bf16_f32 v19, v20, v21
	global_store_dwordx2 v[24:25], v[18:19], off offset:64
	ds_read_b64_tr_b16 v[18:19], v23 offset:96
	ds_read_b64_tr_b16 v[20:21], v23 offset:1184
	ds_read_b64_tr_b16 v[28:29], v23 offset:8800
	ds_read_b64_tr_b16 v[30:31], v23 offset:9888
	s_waitcnt lgkmcnt(2)
	v_mfma_f32_16x16x32_bf16 v[18:21], v[18:21], v[2:5], 0
	s_waitcnt lgkmcnt(0)
	v_mfma_f32_16x16x32_bf16 v[18:21], v[28:31], v[6:9], v[18:21]
	ds_read_b64_tr_b16 v[28:29], v23 offset:17504
	ds_read_b64_tr_b16 v[30:31], v23 offset:18592
	s_waitcnt lgkmcnt(0)
	v_mfma_f32_16x16x32_bf16 v[18:21], v[28:31], v[14:17], v[18:21]
	ds_read_b64_tr_b16 v[28:29], v23 offset:26208
	ds_read_b64_tr_b16 v[30:31], v23 offset:27296
	s_waitcnt lgkmcnt(0)
	v_mfma_f32_16x16x32_bf16 v[18:21], v[28:31], v[10:13], v[18:21]
	s_nop 0
	s_waitcnt vmcnt(7)
	v_lshlrev_b32_e32 v30, 16, v66
	v_and_b32_e32 v31, 0xffff0000, v66
	s_nop 3
	v_pk_add_f32 v[18:19], v[22:23], v[18:19] op_sel_hi:[0,1]
	v_lshlrev_b32_e32 v28, 16, v67
	v_and_b32_e32 v29, 0xffff0000, v67
	v_pk_add_f32 v[20:21], v[22:23], v[20:21] op_sel_hi:[0,1]
	v_pk_mul_f32 v[18:19], v[18:19], v[30:31]
	v_pk_mul_f32 v[20:21], v[20:21], v[28:29]
	v_cvt_pk_bf16_f32 v18, v18, v19
	v_cvt_pk_bf16_f32 v19, v20, v21
	global_store_dwordx2 v[24:25], v[18:19], off offset:96
	ds_read_b64_tr_b16 v[18:19], v23 offset:128
	ds_read_b64_tr_b16 v[20:21], v23 offset:1216
	ds_read_b64_tr_b16 v[28:29], v23 offset:8832
	ds_read_b64_tr_b16 v[30:31], v23 offset:9920
	s_waitcnt lgkmcnt(2)
	v_mfma_f32_16x16x32_bf16 v[18:21], v[18:21], v[2:5], 0
	s_waitcnt lgkmcnt(0)
	v_mfma_f32_16x16x32_bf16 v[18:21], v[28:31], v[6:9], v[18:21]
	ds_read_b64_tr_b16 v[28:29], v23 offset:17536
	ds_read_b64_tr_b16 v[30:31], v23 offset:18624
	s_waitcnt lgkmcnt(0)
	v_mfma_f32_16x16x32_bf16 v[18:21], v[28:31], v[14:17], v[18:21]
	ds_read_b64_tr_b16 v[28:29], v23 offset:26240
	ds_read_b64_tr_b16 v[30:31], v23 offset:27328
	s_waitcnt lgkmcnt(0)
	v_mfma_f32_16x16x32_bf16 v[18:21], v[28:31], v[10:13], v[18:21]
	s_nop 0
	s_waitcnt vmcnt(7)
	v_lshlrev_b32_e32 v30, 16, v68
	v_and_b32_e32 v31, 0xffff0000, v68
	s_nop 3
	v_pk_add_f32 v[18:19], v[22:23], v[18:19] op_sel_hi:[0,1]
	v_lshlrev_b32_e32 v28, 16, v69
	v_and_b32_e32 v29, 0xffff0000, v69
	v_pk_add_f32 v[20:21], v[22:23], v[20:21] op_sel_hi:[0,1]
	v_pk_mul_f32 v[18:19], v[18:19], v[30:31]
	v_pk_mul_f32 v[20:21], v[20:21], v[28:29]
	v_cvt_pk_bf16_f32 v18, v18, v19
	v_cvt_pk_bf16_f32 v19, v20, v21
	global_store_dwordx2 v[24:25], v[18:19], off offset:128
	ds_read_b64_tr_b16 v[18:19], v23 offset:160
	ds_read_b64_tr_b16 v[20:21], v23 offset:1248
	ds_read_b64_tr_b16 v[28:29], v23 offset:8864
	ds_read_b64_tr_b16 v[30:31], v23 offset:9952
	s_waitcnt lgkmcnt(2)
	v_mfma_f32_16x16x32_bf16 v[18:21], v[18:21], v[2:5], 0
	s_waitcnt lgkmcnt(0)
	v_mfma_f32_16x16x32_bf16 v[18:21], v[28:31], v[6:9], v[18:21]
	ds_read_b64_tr_b16 v[28:29], v23 offset:17568
	ds_read_b64_tr_b16 v[30:31], v23 offset:18656
	s_waitcnt lgkmcnt(0)
	v_mfma_f32_16x16x32_bf16 v[18:21], v[28:31], v[14:17], v[18:21]
	ds_read_b64_tr_b16 v[28:29], v23 offset:26272
	ds_read_b64_tr_b16 v[30:31], v23 offset:27360
	s_waitcnt lgkmcnt(0)
	v_mfma_f32_16x16x32_bf16 v[18:21], v[28:31], v[10:13], v[18:21]
	s_nop 0
	s_waitcnt vmcnt(7)
	v_lshlrev_b32_e32 v30, 16, v70
	v_and_b32_e32 v31, 0xffff0000, v70
	s_nop 3
	v_pk_add_f32 v[18:19], v[22:23], v[18:19] op_sel_hi:[0,1]
	v_lshlrev_b32_e32 v28, 16, v71
	v_and_b32_e32 v29, 0xffff0000, v71
	v_pk_add_f32 v[20:21], v[22:23], v[20:21] op_sel_hi:[0,1]
	v_pk_mul_f32 v[18:19], v[18:19], v[30:31]
	v_pk_mul_f32 v[20:21], v[20:21], v[28:29]
	v_cvt_pk_bf16_f32 v18, v18, v19
	v_cvt_pk_bf16_f32 v19, v20, v21
	global_store_dwordx2 v[24:25], v[18:19], off offset:160
	ds_read_b64_tr_b16 v[18:19], v23 offset:192
	ds_read_b64_tr_b16 v[20:21], v23 offset:1280
	ds_read_b64_tr_b16 v[28:29], v23 offset:8896
	ds_read_b64_tr_b16 v[30:31], v23 offset:9984
	s_waitcnt lgkmcnt(2)
	v_mfma_f32_16x16x32_bf16 v[18:21], v[18:21], v[2:5], 0
	s_waitcnt lgkmcnt(0)
	v_mfma_f32_16x16x32_bf16 v[18:21], v[28:31], v[6:9], v[18:21]
	ds_read_b64_tr_b16 v[28:29], v23 offset:17600
	ds_read_b64_tr_b16 v[30:31], v23 offset:18688
	s_waitcnt lgkmcnt(0)
	v_mfma_f32_16x16x32_bf16 v[18:21], v[28:31], v[14:17], v[18:21]
	ds_read_b64_tr_b16 v[28:29], v23 offset:26304
	ds_read_b64_tr_b16 v[30:31], v23 offset:27392
	s_waitcnt lgkmcnt(0)
	v_mfma_f32_16x16x32_bf16 v[18:21], v[28:31], v[10:13], v[18:21]
	s_nop 0
	s_waitcnt vmcnt(7)
	v_lshlrev_b32_e32 v30, 16, v72
	v_and_b32_e32 v31, 0xffff0000, v72
	s_nop 3
	v_pk_add_f32 v[18:19], v[22:23], v[18:19] op_sel_hi:[0,1]
	v_lshlrev_b32_e32 v28, 16, v73
	v_and_b32_e32 v29, 0xffff0000, v73
	v_pk_add_f32 v[20:21], v[22:23], v[20:21] op_sel_hi:[0,1]
	v_pk_mul_f32 v[18:19], v[18:19], v[30:31]
	v_pk_mul_f32 v[20:21], v[20:21], v[28:29]
	v_cvt_pk_bf16_f32 v18, v18, v19
	v_cvt_pk_bf16_f32 v19, v20, v21
	global_store_dwordx2 v[24:25], v[18:19], off offset:192
	ds_read_b64_tr_b16 v[18:19], v23 offset:224
	ds_read_b64_tr_b16 v[20:21], v23 offset:1312
	s_waitcnt lgkmcnt(0)
	v_mfma_f32_16x16x32_bf16 v[2:5], v[18:21], v[2:5], 0
	ds_read_b64_tr_b16 v[18:19], v23 offset:8928
	ds_read_b64_tr_b16 v[20:21], v23 offset:10016
	s_waitcnt lgkmcnt(0)
	v_mfma_f32_16x16x32_bf16 v[2:5], v[18:21], v[6:9], v[2:5]
	ds_read_b64_tr_b16 v[6:7], v23 offset:17632
	ds_read_b64_tr_b16 v[8:9], v23 offset:18720
	s_waitcnt lgkmcnt(0)
	v_mfma_f32_16x16x32_bf16 v[2:5], v[6:9], v[14:17], v[2:5]
	ds_read_b64_tr_b16 v[6:7], v23 offset:26336
	ds_read_b64_tr_b16 v[8:9], v23 offset:27424
	s_waitcnt lgkmcnt(0)
	v_mfma_f32_16x16x32_bf16 v[2:5], v[6:9], v[10:13], v[2:5]
	s_nop 0
	s_waitcnt vmcnt(7)
	v_lshlrev_b32_e32 v8, 16, v74
	v_and_b32_e32 v9, 0xffff0000, v74
	s_nop 3
	v_pk_add_f32 v[2:3], v[22:23], v[2:3] op_sel_hi:[0,1]
	v_lshlrev_b32_e32 v6, 16, v75
	v_and_b32_e32 v7, 0xffff0000, v75
	v_pk_add_f32 v[4:5], v[22:23], v[4:5] op_sel_hi:[0,1]
	v_pk_mul_f32 v[2:3], v[2:3], v[8:9]
	v_pk_mul_f32 v[4:5], v[4:5], v[6:7]
	v_cvt_pk_bf16_f32 v2, v2, v3
	v_cvt_pk_bf16_f32 v3, v4, v5
	global_store_dwordx2 v[24:25], v[2:3], off offset:224
	s_waitcnt lgkmcnt(0)
	s_barrier
